# FFN1 epilogue: staging barrier moved behind the broadcast reads and halo-row stores (wave rows are one barrier apart)
# baseline (speedup 1.0000x reference)
; #define LAS __attribute__((address_space(3)))
;     __device__ __forceinline__ void operator()(AccRef acc, const Unit& u, int wr, int wc, int fr, int fq) const {
;     ...
;         { const float* cv = cw + 128 * u.pn + clb; const float* cg = cv + FH; const float* bp = cb + 128 * u.pn + clb;
;           cwv[0][0] = *(const f32x4*)(cv); cwv[0][1] = *(const f32x4*)(cv + F2); cwv[0][2] = *(const f32x4*)(cv + 2 * F2); cwv[0][3] = *(const f32x4*)(bp);
;           cwv[0][4] = *(const f32x4*)(cg); cwv[0][5] = *(const f32x4*)(cg + F2); cwv[0][6] = *(const f32x4*)(cg + 2 * F2); cwv[0][7] = *(const f32x4*)(bp + FH); }
;         if (fr == 15) {
; #pragma unroll
;             for (int ai = 0; ai < 2; ++ai)
; #pragma unroll
;                 for (int bj = 0; bj < 2; ++bj)
; #pragma unroll
;                     for (int n = 0; n < 2; ++n) { *(LAS f32x4*)(xch + ((ai * 2 + wr) * 2 + 0) * 256 + bj * 128 + clb + 4 * n) = acc[ai][bj][2][n]; *(LAS f32x4*)(xch + ((ai * 2 + wr) * 2 + 1) * 256 + bj * 128 + clb + 4 * n) = acc[ai][bj][3][n]; }
;         }
;         float* rawu = raw + (size_t)(u.pm * 22 + u.pn) * 1024;
;         if (wr == 0 && fr == 0) {
; #pragma unroll
;             for (int bj = 0; bj < 2; ++bj)
; #pragma unroll
;                 for (int n = 0; n < 2; ++n) { *(f32x4*)(rawu + 0 * 256 + bj * 128 + clb + 4 * n) = acc[0][bj][0][n]; *(f32x4*)(rawu + 1 * 256 + bj * 128 + clb + 4 * n) = acc[0][bj][1][n]; }
;         }
;         if (wr == 1 && fr == 15) {
; #pragma unroll
;             for (int bj = 0; bj < 2; ++bj)
; #pragma unroll
;                 for (int n = 0; n < 2; ++n) { *(f32x4*)(rawu + 2 * 256 + bj * 128 + clb + 4 * n) = acc[1][bj][2][n]; *(f32x4*)(rawu + 3 * 256 + bj * 128 + clb + 4 * n) = acc[1][bj][3][n]; }
;         }
;         asm volatile("s_waitcnt lgkmcnt(0)" ::: "memory"); __builtin_amdgcn_s_barrier(); __builtin_amdgcn_s_barrier(); asm volatile("" ::: "memory");
.Lcw309_nostage:
	v_and_b32_e32 v253, 0xf0, v219
	v_lshlrev_b32_e32 v253, 4, v253
	v_add_u32_e32 v253, 0x22000, v253
	ds_read_b128 v[160:163], v253
	ds_read_b128 v[164:167], v253 offset:16
	ds_read_b128 v[168:171], v253 offset:32
	ds_read_b128 v[172:175], v253 offset:48
	ds_read_b128 v[176:179], v253 offset:64
	ds_read_b128 v[180:183], v253 offset:80
	ds_read_b128 v[184:187], v253 offset:96
	ds_read_b128 v[188:191], v253 offset:112
	ds_read_b128 v[96:99], v253 offset:128
	ds_read_b128 v[100:103], v253 offset:144
	ds_read_b128 v[104:107], v253 offset:160
	ds_read_b128 v[108:111], v253 offset:176
	ds_read_b128 v[112:115], v253 offset:192
	ds_read_b128 v[116:119], v253 offset:208
	ds_read_b128 v[120:123], v253 offset:224
	ds_read_b128 v[124:127], v253 offset:240
	s_waitcnt lgkmcnt(0)
	v_lshlrev_b32_e32 v253, 2, v218
	s_and_saveexec_b64 s[40:41], s[10:11]
	s_cbranch_execz .LBB0_314
	global_store_dwordx4 v253, v[156:159], s[38:39]
	global_store_dwordx4 v253, v[144:147], s[38:39] offset:1024
	global_store_dwordx4 v253, v[60:63], s[38:39] offset:16
	global_store_dwordx4 v253, v[48:51], s[38:39] offset:1040
	global_store_dwordx4 v253, v[152:155], s[38:39] offset:512
	global_store_dwordx4 v253, v[132:135], s[38:39] offset:1536
	global_store_dwordx4 v253, v[56:59], s[38:39] offset:528
	global_store_dwordx4 v253, v[36:39], s[38:39] offset:1552

; #define LAS __attribute__((address_space(3)))
;     __device__ __forceinline__ void operator()(AccRef acc, const Unit& u, int wr, int wc, int fr, int fq) const {
;     ...
;         asm volatile("s_waitcnt lgkmcnt(0)" ::: "memory"); __builtin_amdgcn_s_barrier(); __builtin_amdgcn_s_barrier(); asm volatile("" ::: "memory");
;         const int hc0 = 128 * u.pn + clb, row0 = u.pm * 256 + wr * 64 + 4 * fr;
; #pragma unroll
;         for (int n = 0; n < 2; ++n) {
;             const f32x4 w0v = cwv[n][0], w1v = cwv[n][1], w2v = cwv[n][2], bvv = cwv[n][3], w0g = cwv[n][4], w1g = cwv[n][5], w2g = cwv[n][6], bvg = cwv[n][7];
; #pragma unroll
;             for (int ai = 0; ai < 2; ++ai) {
;                 if (n == 0 && ai == 0) {
;                     asm volatile("" ::: "memory");
;                     const float* cv = cw + hc0 + 4; const float* cg = cv + FH; const float* bp = cb + hc0 + 4;
;                     cwv[1][0] = *(const f32x4*)(cv); cwv[1][1] = *(const f32x4*)(cv + F2); cwv[1][2] = *(const f32x4*)(cv + 2 * F2); cwv[1][3] = *(const f32x4*)(bp);
;                     cwv[1][4] = *(const f32x4*)(cg); cwv[1][5] = *(const f32x4*)(cg + F2); cwv[1][6] = *(const f32x4*)(cg + 2 * F2); cwv[1][7] = *(const f32x4*)(bp + FH);
;                     asm volatile("" ::: "memory"); }
;                 f32x4 h2v = (f32x4){0.f, 0.f, 0.f, 0.f}, h3v = h2v, h2g = h2v, h3g = h2v;
;                 const int pb = ai * 2 + wr - 1;
;                 if (pb >= 0 && fr == 0) { const LAS float* xp = xch + (pb * 2) * 256 + clb + 4 * n;
;                     h2v = *(const LAS f32x4*)(xp); h3v = *(const LAS f32x4*)(xp + 256); h2g = *(const LAS f32x4*)(xp + 128); h3g = *(const LAS f32x4*)(xp + 256 + 128); }
;                 float o[4][4];
; #pragma unroll
;                 for (int j = 0; j < 4; ++j) {
;                     const float v0 = acc[ai][0][0][n][j], v1 = acc[ai][0][1][n][j], v2 = acc[ai][0][2][n][j], v3 = acc[ai][0][3][n][j];
;                     const float g0 = acc[ai][1][0][n][j], g1 = acc[ai][1][1][n][j], g2 = acc[ai][1][2][n][j], g3 = acc[ai][1][3][n][j];
;                     const float pv3 = dpp_upd<0x111>(h3v[j], v3), pv2 = dpp_upd<0x111>(h2v[j], v2), pg3 = dpp_upd<0x111>(h3g[j], g3), pg2 = dpp_upd<0x111>(h2g[j], g2);
;                     const float hv0 = bvv[j] + w2v[j] * v0 + w1v[j] * pv3 + w0v[j] * pv2, hv1 = bvv[j] + w2v[j] * v1 + w1v[j] * v0 + w0v[j] * pv3;
.LBB0_316:
	s_or_b64 exec, exec, s[40:41]
	s_barrier
	v_pk_fma_f32 v[248:249], v[152:153], v[184:185], v[188:189]
	v_mov_b32_dpp v206, v128 row_shr:1 row_mask:0xf bank_mask:0xf
	v_mov_b32_dpp v207, v129 row_shr:1 row_mask:0xf bank_mask:0xf
	v_pk_fma_f32 v[248:249], v[180:181], v[198:199], v[248:249]
	v_mov_b32_dpp v194, v148 row_shr:1 row_mask:0xf bank_mask:0xf
	v_pk_fma_f32 v[206:207], v[176:177], v[206:207], v[248:249]
	v_mov_b32_dpp v195, v149 row_shr:1 row_mask:0xf bank_mask:0xf
	v_exp_f32_e32 v248, v206
	v_exp_f32_e32 v249, v207
	v_pk_fma_f32 v[250:251], v[156:157], v[168:169], v[172:173]
	v_pk_add_f32 v[248:249], v[248:249], 1.0 op_sel_hi:[1,0]
	v_rcp_f32_e32 v248, v248
	v_rcp_f32_e32 v249, v249
	v_mov_b32_dpp v202, v136 row_shr:1 row_mask:0xf bank_mask:0xf
	v_mov_b32_dpp v203, v137 row_shr:1 row_mask:0xf bank_mask:0xf
	v_pk_fma_f32 v[250:251], v[164:165], v[194:195], v[250:251]
	v_pk_mul_f32 v[206:207], v[206:207], v[248:249]
	v_pk_fma_f32 v[202:203], v[160:161], v[202:203], v[250:251]
	v_mov_b32_dpp v200, v142 row_shr:1 row_mask:0xf bank_mask:0xf
	v_mov_b32_dpp v201, v143 row_shr:1 row_mask:0xf bank_mask:0xf
	v_pk_mul_f32 v[202:203], v[202:203], v[206:207]
	v_pk_fma_f32 v[206:207], v[154:155], v[186:187], v[190:191]
	v_mov_b32_dpp v208, v130 row_shr:1 row_mask:0xf bank_mask:0xf
	v_mov_b32_dpp v209, v131 row_shr:1 row_mask:0xf bank_mask:0xf
	v_pk_fma_f32 v[206:207], v[182:183], v[200:201], v[206:207]
	v_mov_b32_dpp v196, v150 row_shr:1 row_mask:0xf bank_mask:0xf
	v_pk_fma_f32 v[206:207], v[178:179], v[208:209], v[206:207]
	v_mov_b32_dpp v197, v151 row_shr:1 row_mask:0xf bank_mask:0xf
	v_exp_f32_e32 v193, v206
	v_exp_f32_e32 v209, v207
	v_cvt_pk_bf16_f32 v247, v202, v203
	v_add_f32_e32 v193, 1.0, v193
	v_rcp_f32_e32 v202, v193
	v_add_f32_e32 v193, 1.0, v209
	v_rcp_f32_e32 v203, v193
	v_pk_fma_f32 v[248:249], v[158:159], v[170:171], v[174:175]
	v_mov_b32_dpp v204, v138 row_shr:1 row_mask:0xf bank_mask:0xf
	v_mov_b32_dpp v205, v139 row_shr:1 row_mask:0xf bank_mask:0xf
	v_pk_fma_f32 v[248:249], v[166:167], v[196:197], v[248:249]
	v_pk_mul_f32 v[202:203], v[206:207], v[202:203]
	v_pk_fma_f32 v[204:205], v[162:163], v[204:205], v[248:249]
	v_lshl_add_u32 v246, s34, 8, v236
	v_pk_mul_f32 v[202:203], v[204:205], v[202:203]
	v_lshlrev_b64 v[204:205], 1, v[232:233]
	v_pk_fma_f32 v[232:233], v[132:133], v[184:185], v[188:189]
	v_mov_b64_e32 v[206:207], s[60:61]
	v_pk_fma_f32 v[232:233], v[152:153], v[180:181], v[232:233]
	v_cvt_pk_bf16_f32 v248, v202, v203
	v_pk_fma_f32 v[198:199], v[176:177], v[198:199], v[232:233]
	v_mad_i64_i32 v[202:203], s[34:35], v246, s74, v[206:207]
	v_exp_f32_e32 v193, v198
	v_exp_f32_e32 v232, v199
	v_lshl_add_u64 v[202:203], v[202:203], 0, v[204:205]
	v_add_f32_e32 v193, 1.0, v193
	v_rcp_f32_e32 v208, v193
	v_add_f32_e32 v193, 1.0, v232
	v_rcp_f32_e32 v209, v193
	v_pk_fma_f32 v[232:233], v[144:145], v[168:169], v[172:173]
	v_pk_fma_f32 v[140:141], v[140:141], v[184:185], v[188:189]
	v_pk_fma_f32 v[232:233], v[156:157], v[164:165], v[232:233]
	v_pk_mul_f32 v[198:199], v[198:199], v[208:209]
	v_pk_fma_f32 v[194:195], v[160:161], v[194:195], v[232:233]
	v_pk_fma_f32 v[208:209], v[146:147], v[170:171], v[174:175]
	v_pk_mul_f32 v[194:195], v[194:195], v[198:199]
	v_pk_fma_f32 v[198:199], v[134:135], v[186:187], v[190:191]
	v_pk_fma_f32 v[208:209], v[158:159], v[166:167], v[208:209]
	v_pk_fma_f32 v[198:199], v[154:155], v[182:183], v[198:199]
	v_pk_fma_f32 v[196:197], v[162:163], v[196:197], v[208:209]
	v_pk_fma_f32 v[198:199], v[178:179], v[200:201], v[198:199]
	v_cvt_pk_bf16_f32 v249, v194, v195
	v_exp_f32_e32 v200, v198
	v_exp_f32_e32 v201, v199
	v_pk_fma_f32 v[148:149], v[148:149], v[168:169], v[172:173]
; #define LAS __attribute__((address_space(3)))
; __device__ __forceinline__ float sigmoidf_(float x) { return __builtin_amdgcn_rcpf(1.0f + __expf(-x)); }
;     __device__ __forceinline__ void operator()(AccRef acc, const Unit& u, int wr, int wc, int fr, int fq) const {
;     ...
;                 f32x4 h2v = (f32x4){0.f, 0.f, 0.f, 0.f}, h3v = h2v, h2g = h2v, h3g = h2v;
;                 const int pb = ai * 2 + wr - 1;
;                 if (pb >= 0 && fr == 0) { const LAS float* xp = xch + (pb * 2) * 256 + clb + 4 * n;
;                     h2v = *(const LAS f32x4*)(xp); h3v = *(const LAS f32x4*)(xp + 256); h2g = *(const LAS f32x4*)(xp + 128); h3g = *(const LAS f32x4*)(xp + 256 + 128); }
;                 float o[4][4];
; #pragma unroll
;                 for (int j = 0; j < 4; ++j) {
;                     const float v0 = acc[ai][0][0][n][j], v1 = acc[ai][0][1][n][j], v2 = acc[ai][0][2][n][j], v3 = acc[ai][0][3][n][j];
;                     const float g0 = acc[ai][1][0][n][j], g1 = acc[ai][1][1][n][j], g2 = acc[ai][1][2][n][j], g3 = acc[ai][1][3][n][j];
;                     const float pv3 = dpp_upd<0x111>(h3v[j], v3), pv2 = dpp_upd<0x111>(h2v[j], v2), pg3 = dpp_upd<0x111>(h3g[j], g3), pg2 = dpp_upd<0x111>(h2g[j], g2);
;                     const float hv0 = bvv[j] + w2v[j] * v0 + w1v[j] * pv3 + w0v[j] * pv2, hv1 = bvv[j] + w2v[j] * v1 + w1v[j] * v0 + w0v[j] * pv3;
;                     const float hv2 = bvv[j] + w2v[j] * v2 + w1v[j] * v1 + w0v[j] * v0, hv3 = bvv[j] + w2v[j] * v3 + w1v[j] * v2 + w0v[j] * v1;
;                     const float hg0 = bvg[j] + w2g[j] * g0 + w1g[j] * pg3 + w0g[j] * pg2, hg1 = bvg[j] + w2g[j] * g1 + w1g[j] * g0 + w0g[j] * pg3;
;                     const float hg2 = bvg[j] + w2g[j] * g2 + w1g[j] * g1 + w0g[j] * g0, hg3 = bvg[j] + w2g[j] * g3 + w1g[j] * g2 + w0g[j] * g1;
;                     o[0][j] = hg0 * sigmoidf_(hg0) * hv0; o[1][j] = hg1 * sigmoidf_(hg1) * hv1; o[2][j] = hg2 * sigmoidf_(hg2) * hv2; o[3][j] = hg3 * sigmoidf_(hg3) * hv3; }
; #pragma unroll
;                 for (int m = 0; m < 4; ++m) { u32x2 w; w.x = cvt_pk_bf16(o[m][0], o[m][1]); w.y = cvt_pk_bf16(o[m][2], o[m][3]);
;                     *(u32x2*)(Aout + (size_t)(row0 + ai * 128 + m) * FH + hc0 + 4 * n) = w; } } }
	v_pk_add_f32 v[200:201], v[200:201], 1.0 op_sel_hi:[1,0]
	v_rcp_f32_e32 v200, v200
	v_rcp_f32_e32 v201, v201
	v_or_b32_e32 v193, 1, v246
	v_pk_mul_f32 v[198:199], v[198:199], v[200:201]
	s_nop 0
	v_pk_mul_f32 v[196:197], v[196:197], v[198:199]
	v_pk_fma_f32 v[198:199], v[128:129], v[184:185], v[188:189]
	v_cvt_pk_bf16_f32 v250, v196, v197
	v_pk_fma_f32 v[198:199], v[132:133], v[180:181], v[198:199]
	v_mad_i64_i32 v[196:197], s[34:35], v193, s74, v[206:207]
	v_pk_fma_f32 v[152:153], v[152:153], v[176:177], v[198:199]
	v_lshl_add_u64 v[196:197], v[196:197], 0, v[204:205]
	v_exp_f32_e32 v193, v152
	v_exp_f32_e32 v198, v153
	v_add_f32_e32 v193, 1.0, v193
	v_rcp_f32_e32 v194, v193
	v_add_f32_e32 v193, 1.0, v198
	v_rcp_f32_e32 v195, v193
	v_pk_fma_f32 v[198:199], v[136:137], v[168:169], v[172:173]
	v_pk_fma_f32 v[128:129], v[128:129], v[180:181], v[140:141]
	v_pk_fma_f32 v[198:199], v[144:145], v[164:165], v[198:199]
	v_pk_fma_f32 v[128:129], v[132:133], v[176:177], v[128:129]
	v_pk_fma_f32 v[156:157], v[156:157], v[160:161], v[198:199]
	v_pk_mul_f32 v[152:153], v[152:153], v[194:195]
	v_pk_mul_f32 v[152:153], v[156:157], v[152:153]
	v_pk_fma_f32 v[156:157], v[130:131], v[186:187], v[190:191]
	v_exp_f32_e32 v140, v128
	v_pk_fma_f32 v[132:133], v[142:143], v[186:187], v[190:191]
	v_pk_fma_f32 v[156:157], v[134:135], v[182:183], v[156:157]
	v_pk_fma_f32 v[130:131], v[130:131], v[182:183], v[132:133]
	v_pk_fma_f32 v[154:155], v[154:155], v[178:179], v[156:157]
	v_pk_fma_f32 v[130:131], v[134:135], v[178:179], v[130:131]
	v_exp_f32_e32 v157, v154
	v_exp_f32_e32 v141, v129
	v_exp_f32_e32 v132, v130
	v_exp_f32_e32 v133, v131
	v_exp_f32_e32 v193, v155
	v_pk_add_f32 v[140:141], v[140:141], 1.0 op_sel_hi:[1,0]
	v_pk_add_f32 v[132:133], v[132:133], 1.0 op_sel_hi:[1,0]
	v_cvt_pk_bf16_f32 v254, v152, v153
	v_add_f32_e32 v152, 1.0, v157
	v_add_f32_e32 v153, 1.0, v193
	v_rcp_f32_e32 v140, v140
	v_rcp_f32_e32 v141, v141
	v_rcp_f32_e32 v132, v132
	v_rcp_f32_e32 v133, v133
	v_rcp_f32_e32 v152, v152
	v_rcp_f32_e32 v153, v153
	v_pk_fma_f32 v[142:143], v[150:151], v[170:171], v[174:175]
	v_pk_fma_f32 v[194:195], v[138:139], v[170:171], v[174:175]
	v_pk_fma_f32 v[136:137], v[136:137], v[164:165], v[148:149]
	v_pk_fma_f32 v[134:135], v[138:139], v[166:167], v[142:143]
	v_pk_fma_f32 v[194:195], v[146:147], v[166:167], v[194:195]
	v_pk_fma_f32 v[136:137], v[144:145], v[160:161], v[136:137]
	v_pk_mul_f32 v[128:129], v[128:129], v[140:141]
	v_pk_fma_f32 v[134:135], v[146:147], v[162:163], v[134:135]
	v_pk_mul_f32 v[130:131], v[130:131], v[132:133]
	v_pk_fma_f32 v[158:159], v[158:159], v[162:163], v[194:195]
	v_pk_mul_f32 v[152:153], v[154:155], v[152:153]
	v_pk_mul_f32 v[128:129], v[136:137], v[128:129]
	v_pk_mul_f32 v[130:131], v[134:135], v[130:131]
	v_pk_mul_f32 v[152:153], v[158:159], v[152:153]
	v_cvt_pk_bf16_f32 v251, v128, v129
	v_cvt_pk_bf16_f32 v253, v130, v131
	v_or_b32_e32 v130, 3, v246
	v_cvt_pk_bf16_f32 v255, v152, v153
	v_or_b32_e32 v152, 2, v246
	v_mad_i64_i32 v[130:131], s[34:35], v130, s74, v[206:207]
	v_mad_i64_i32 v[152:153], s[34:35], v152, s74, v[206:207]
	v_lshl_add_u64 v[140:141], v[130:131], 0, v[204:205]
	v_lshl_add_u64 v[152:153], v[152:153], 0, v[204:205]
	v_mov_b32_e32 v193, 0
	v_mov_b64_e32 v[194:195], 0
	v_mov_b64_e32 v[136:137], 0
	v_mov_b64_e32 v[138:139], 0
	v_mov_b64_e32 v[128:129], 0
	v_mov_b64_e32 v[130:131], 0
	v_mov_b64_e32 v[132:133], 0
	v_mov_b64_e32 v[134:135], 0
	s_and_saveexec_b64 s[34:35], s[22:23]
	s_cbranch_execz .LBB0_320
	ds_read_b128 v[132:135], v237 offset:2048
	ds_read_b128 v[136:139], v237 offset:2560
	ds_read_b128 v[128:131], v237 offset:3072
	ds_read_b128 v[192:195], v237 offset:3584

; #define LAS __attribute__((address_space(3)))
;     __device__ __forceinline__ void operator()(AccRef acc, const Unit& u, int wr, int wc, int fr, int fq) const {
;     ...
;         { const float* cv = cw + 128 * u.pn + clb; const float* cg = cv + FH; const float* bp = cb + 128 * u.pn + clb;
;           cwv[0][0] = *(const f32x4*)(cv); cwv[0][1] = *(const f32x4*)(cv + F2); cwv[0][2] = *(const f32x4*)(cv + 2 * F2); cwv[0][3] = *(const f32x4*)(bp);
;           cwv[0][4] = *(const f32x4*)(cg); cwv[0][5] = *(const f32x4*)(cg + F2); cwv[0][6] = *(const f32x4*)(cg + 2 * F2); cwv[0][7] = *(const f32x4*)(bp + FH); }
;         if (fr == 15) {
; #pragma unroll
;             for (int ai = 0; ai < 2; ++ai)
; #pragma unroll
;                 for (int bj = 0; bj < 2; ++bj)
; #pragma unroll
;                     for (int n = 0; n < 2; ++n) { *(LAS f32x4*)(xch + ((ai * 2 + wr) * 2 + 0) * 256 + bj * 128 + clb + 4 * n) = acc[ai][bj][2][n]; *(LAS f32x4*)(xch + ((ai * 2 + wr) * 2 + 1) * 256 + bj * 128 + clb + 4 * n) = acc[ai][bj][3][n]; }
;         }
;         float* rawu = raw + (size_t)(u.pm * 22 + u.pn) * 1024;
;         if (wr == 0 && fr == 0) {
; #pragma unroll
;             for (int bj = 0; bj < 2; ++bj)
; #pragma unroll
;                 for (int n = 0; n < 2; ++n) { *(f32x4*)(rawu + 0 * 256 + bj * 128 + clb + 4 * n) = acc[0][bj][0][n]; *(f32x4*)(rawu + 1 * 256 + bj * 128 + clb + 4 * n) = acc[0][bj][1][n]; }
;         }
;         if (wr == 1 && fr == 15) {
; #pragma unroll
;             for (int bj = 0; bj < 2; ++bj)
; #pragma unroll
;                 for (int n = 0; n < 2; ++n) { *(f32x4*)(rawu + 2 * 256 + bj * 128 + clb + 4 * n) = acc[1][bj][2][n]; *(f32x4*)(rawu + 3 * 256 + bj * 128 + clb + 4 * n) = acc[1][bj][3][n]; }
;         }
;         asm volatile("s_waitcnt lgkmcnt(0)" ::: "memory"); __builtin_amdgcn_s_barrier(); __builtin_amdgcn_s_barrier(); asm volatile("" ::: "memory");
.Lcw758_nostage:
	v_and_b32_e32 v253, 0xf0, v219
	v_lshlrev_b32_e32 v253, 4, v253
	v_add_u32_e32 v253, 0x22000, v253
	ds_read_b128 v[160:163], v253
	ds_read_b128 v[164:167], v253 offset:16
	ds_read_b128 v[168:171], v253 offset:32
	ds_read_b128 v[172:175], v253 offset:48
	ds_read_b128 v[176:179], v253 offset:64
	ds_read_b128 v[180:183], v253 offset:80
	ds_read_b128 v[184:187], v253 offset:96
	ds_read_b128 v[188:191], v253 offset:112
	ds_read_b128 v[96:99], v253 offset:128
	ds_read_b128 v[100:103], v253 offset:144
	ds_read_b128 v[104:107], v253 offset:160
	ds_read_b128 v[108:111], v253 offset:176
	ds_read_b128 v[112:115], v253 offset:192
	ds_read_b128 v[116:119], v253 offset:208
	ds_read_b128 v[120:123], v253 offset:224
	ds_read_b128 v[124:127], v253 offset:240
	s_waitcnt lgkmcnt(0)
	v_lshlrev_b32_e32 v253, 2, v218
	s_and_saveexec_b64 s[46:47], s[12:13]
	s_cbranch_execz .LBB0_763
	global_store_dwordx4 v253, v[156:159], s[44:45]
	global_store_dwordx4 v253, v[144:147], s[44:45] offset:1024
	global_store_dwordx4 v253, v[60:63], s[44:45] offset:16
	global_store_dwordx4 v253, v[48:51], s[44:45] offset:1040
	global_store_dwordx4 v253, v[152:155], s[44:45] offset:512
	global_store_dwordx4 v253, v[132:135], s[44:45] offset:1536
	global_store_dwordx4 v253, v[56:59], s[44:45] offset:528
	global_store_dwordx4 v253, v[36:39], s[44:45] offset:1552

; #define LAS __attribute__((address_space(3)))
;     __device__ __forceinline__ void operator()(AccRef acc, const Unit& u, int wr, int wc, int fr, int fq) const {
;     ...
;         asm volatile("s_waitcnt lgkmcnt(0)" ::: "memory"); __builtin_amdgcn_s_barrier(); __builtin_amdgcn_s_barrier(); asm volatile("" ::: "memory");
;         const int hc0 = 128 * u.pn + clb, row0 = u.pm * 256 + wr * 64 + 4 * fr;
; #pragma unroll
;         for (int n = 0; n < 2; ++n) {
;             const f32x4 w0v = cwv[n][0], w1v = cwv[n][1], w2v = cwv[n][2], bvv = cwv[n][3], w0g = cwv[n][4], w1g = cwv[n][5], w2g = cwv[n][6], bvg = cwv[n][7];
; #pragma unroll
;             for (int ai = 0; ai < 2; ++ai) {
;                 if (n == 0 && ai == 0) {
;                     asm volatile("" ::: "memory");
;                     const float* cv = cw + hc0 + 4; const float* cg = cv + FH; const float* bp = cb + hc0 + 4;
;                     cwv[1][0] = *(const f32x4*)(cv); cwv[1][1] = *(const f32x4*)(cv + F2); cwv[1][2] = *(const f32x4*)(cv + 2 * F2); cwv[1][3] = *(const f32x4*)(bp);
;                     cwv[1][4] = *(const f32x4*)(cg); cwv[1][5] = *(const f32x4*)(cg + F2); cwv[1][6] = *(const f32x4*)(cg + 2 * F2); cwv[1][7] = *(const f32x4*)(bp + FH);
;                     asm volatile("" ::: "memory"); }
;                 f32x4 h2v = (f32x4){0.f, 0.f, 0.f, 0.f}, h3v = h2v, h2g = h2v, h3g = h2v;
;                 const int pb = ai * 2 + wr - 1;
;                 if (pb >= 0 && fr == 0) { const LAS float* xp = xch + (pb * 2) * 256 + clb + 4 * n;
;                     h2v = *(const LAS f32x4*)(xp); h3v = *(const LAS f32x4*)(xp + 256); h2g = *(const LAS f32x4*)(xp + 128); h3g = *(const LAS f32x4*)(xp + 256 + 128); }
;                 float o[4][4];
; #pragma unroll
;                 for (int j = 0; j < 4; ++j) {
;                     const float v0 = acc[ai][0][0][n][j], v1 = acc[ai][0][1][n][j], v2 = acc[ai][0][2][n][j], v3 = acc[ai][0][3][n][j];
;                     const float g0 = acc[ai][1][0][n][j], g1 = acc[ai][1][1][n][j], g2 = acc[ai][1][2][n][j], g3 = acc[ai][1][3][n][j];
;                     const float pv3 = dpp_upd<0x111>(h3v[j], v3), pv2 = dpp_upd<0x111>(h2v[j], v2), pg3 = dpp_upd<0x111>(h3g[j], g3), pg2 = dpp_upd<0x111>(h2g[j], g2);
;                     const float hv0 = bvv[j] + w2v[j] * v0 + w1v[j] * pv3 + w0v[j] * pv2, hv1 = bvv[j] + w2v[j] * v1 + w1v[j] * v0 + w0v[j] * pv3;
.LBB0_765:
	s_or_b64 exec, exec, s[46:47]
	s_barrier
	v_pk_fma_f32 v[248:249], v[152:153], v[184:185], v[188:189]
	v_mov_b32_dpp v206, v128 row_shr:1 row_mask:0xf bank_mask:0xf
	v_mov_b32_dpp v207, v129 row_shr:1 row_mask:0xf bank_mask:0xf
	v_pk_fma_f32 v[248:249], v[180:181], v[198:199], v[248:249]
	v_mov_b32_dpp v194, v148 row_shr:1 row_mask:0xf bank_mask:0xf
	v_pk_fma_f32 v[206:207], v[176:177], v[206:207], v[248:249]
	v_mov_b32_dpp v195, v149 row_shr:1 row_mask:0xf bank_mask:0xf
	v_exp_f32_e32 v248, v206
	v_exp_f32_e32 v249, v207
	v_pk_fma_f32 v[250:251], v[156:157], v[168:169], v[172:173]
	v_pk_add_f32 v[248:249], v[248:249], 1.0 op_sel_hi:[1,0]
	v_rcp_f32_e32 v248, v248
	v_rcp_f32_e32 v249, v249
	v_mov_b32_dpp v202, v136 row_shr:1 row_mask:0xf bank_mask:0xf
	v_mov_b32_dpp v203, v137 row_shr:1 row_mask:0xf bank_mask:0xf
	v_pk_fma_f32 v[250:251], v[164:165], v[194:195], v[250:251]
	v_pk_mul_f32 v[206:207], v[206:207], v[248:249]
	v_pk_fma_f32 v[202:203], v[160:161], v[202:203], v[250:251]
	v_mov_b32_dpp v200, v142 row_shr:1 row_mask:0xf bank_mask:0xf
	v_mov_b32_dpp v201, v143 row_shr:1 row_mask:0xf bank_mask:0xf
	v_pk_mul_f32 v[202:203], v[202:203], v[206:207]
	v_pk_fma_f32 v[206:207], v[154:155], v[186:187], v[190:191]
	v_mov_b32_dpp v208, v130 row_shr:1 row_mask:0xf bank_mask:0xf
	v_mov_b32_dpp v209, v131 row_shr:1 row_mask:0xf bank_mask:0xf
	v_pk_fma_f32 v[206:207], v[182:183], v[200:201], v[206:207]
	v_mov_b32_dpp v196, v150 row_shr:1 row_mask:0xf bank_mask:0xf
	v_pk_fma_f32 v[206:207], v[178:179], v[208:209], v[206:207]
	v_mov_b32_dpp v197, v151 row_shr:1 row_mask:0xf bank_mask:0xf
	v_exp_f32_e32 v193, v206
	v_exp_f32_e32 v209, v207
	v_cvt_pk_bf16_f32 v247, v202, v203
	v_add_f32_e32 v193, 1.0, v193
	v_rcp_f32_e32 v202, v193
	v_add_f32_e32 v193, 1.0, v209
	v_rcp_f32_e32 v203, v193
	v_pk_fma_f32 v[248:249], v[158:159], v[170:171], v[174:175]
	v_mov_b32_dpp v204, v138 row_shr:1 row_mask:0xf bank_mask:0xf
	v_mov_b32_dpp v205, v139 row_shr:1 row_mask:0xf bank_mask:0xf
	v_pk_fma_f32 v[248:249], v[166:167], v[196:197], v[248:249]
	v_pk_mul_f32 v[202:203], v[206:207], v[202:203]
	v_pk_fma_f32 v[204:205], v[162:163], v[204:205], v[248:249]
	v_lshl_add_u32 v246, s40, 8, v236
	v_pk_mul_f32 v[202:203], v[204:205], v[202:203]
	v_lshlrev_b64 v[204:205], 1, v[232:233]
	v_pk_fma_f32 v[232:233], v[132:133], v[184:185], v[188:189]
	v_mov_b64_e32 v[206:207], s[60:61]
	v_pk_fma_f32 v[232:233], v[152:153], v[180:181], v[232:233]
	v_cvt_pk_bf16_f32 v248, v202, v203
	v_pk_fma_f32 v[198:199], v[176:177], v[198:199], v[232:233]
	v_mad_i64_i32 v[202:203], s[40:41], v246, s76, v[206:207]
	v_exp_f32_e32 v193, v198
	v_exp_f32_e32 v232, v199
	v_lshl_add_u64 v[202:203], v[202:203], 0, v[204:205]
	v_add_f32_e32 v193, 1.0, v193
	v_rcp_f32_e32 v208, v193
	v_add_f32_e32 v193, 1.0, v232
	v_rcp_f32_e32 v209, v193
	v_pk_fma_f32 v[232:233], v[144:145], v[168:169], v[172:173]
	v_pk_fma_f32 v[140:141], v[140:141], v[184:185], v[188:189]
	v_pk_fma_f32 v[232:233], v[156:157], v[164:165], v[232:233]
	v_pk_mul_f32 v[198:199], v[198:199], v[208:209]
	v_pk_fma_f32 v[194:195], v[160:161], v[194:195], v[232:233]
	v_pk_fma_f32 v[208:209], v[146:147], v[170:171], v[174:175]
	v_pk_mul_f32 v[194:195], v[194:195], v[198:199]
	v_pk_fma_f32 v[198:199], v[134:135], v[186:187], v[190:191]
	v_pk_fma_f32 v[208:209], v[158:159], v[166:167], v[208:209]
	v_pk_fma_f32 v[198:199], v[154:155], v[182:183], v[198:199]
	v_pk_fma_f32 v[196:197], v[162:163], v[196:197], v[208:209]
	v_pk_fma_f32 v[198:199], v[178:179], v[200:201], v[198:199]
	v_cvt_pk_bf16_f32 v249, v194, v195
	v_exp_f32_e32 v200, v198
	v_exp_f32_e32 v201, v199
	v_pk_fma_f32 v[148:149], v[148:149], v[168:169], v[172:173]
; #define LAS __attribute__((address_space(3)))
; __device__ __forceinline__ float sigmoidf_(float x) { return __builtin_amdgcn_rcpf(1.0f + __expf(-x)); }
;     __device__ __forceinline__ void operator()(AccRef acc, const Unit& u, int wr, int wc, int fr, int fq) const {
;     ...
;                 f32x4 h2v = (f32x4){0.f, 0.f, 0.f, 0.f}, h3v = h2v, h2g = h2v, h3g = h2v;
;                 const int pb = ai * 2 + wr - 1;
;                 if (pb >= 0 && fr == 0) { const LAS float* xp = xch + (pb * 2) * 256 + clb + 4 * n;
;                     h2v = *(const LAS f32x4*)(xp); h3v = *(const LAS f32x4*)(xp + 256); h2g = *(const LAS f32x4*)(xp + 128); h3g = *(const LAS f32x4*)(xp + 256 + 128); }
;                 float o[4][4];
; #pragma unroll
;                 for (int j = 0; j < 4; ++j) {
;                     const float v0 = acc[ai][0][0][n][j], v1 = acc[ai][0][1][n][j], v2 = acc[ai][0][2][n][j], v3 = acc[ai][0][3][n][j];
;                     const float g0 = acc[ai][1][0][n][j], g1 = acc[ai][1][1][n][j], g2 = acc[ai][1][2][n][j], g3 = acc[ai][1][3][n][j];
;                     const float pv3 = dpp_upd<0x111>(h3v[j], v3), pv2 = dpp_upd<0x111>(h2v[j], v2), pg3 = dpp_upd<0x111>(h3g[j], g3), pg2 = dpp_upd<0x111>(h2g[j], g2);
;                     const float hv0 = bvv[j] + w2v[j] * v0 + w1v[j] * pv3 + w0v[j] * pv2, hv1 = bvv[j] + w2v[j] * v1 + w1v[j] * v0 + w0v[j] * pv3;
;                     const float hv2 = bvv[j] + w2v[j] * v2 + w1v[j] * v1 + w0v[j] * v0, hv3 = bvv[j] + w2v[j] * v3 + w1v[j] * v2 + w0v[j] * v1;
;                     const float hg0 = bvg[j] + w2g[j] * g0 + w1g[j] * pg3 + w0g[j] * pg2, hg1 = bvg[j] + w2g[j] * g1 + w1g[j] * g0 + w0g[j] * pg3;
;                     const float hg2 = bvg[j] + w2g[j] * g2 + w1g[j] * g1 + w0g[j] * g0, hg3 = bvg[j] + w2g[j] * g3 + w1g[j] * g2 + w0g[j] * g1;
;                     o[0][j] = hg0 * sigmoidf_(hg0) * hv0; o[1][j] = hg1 * sigmoidf_(hg1) * hv1; o[2][j] = hg2 * sigmoidf_(hg2) * hv2; o[3][j] = hg3 * sigmoidf_(hg3) * hv3; }
; #pragma unroll
;                 for (int m = 0; m < 4; ++m) { u32x2 w; w.x = cvt_pk_bf16(o[m][0], o[m][1]); w.y = cvt_pk_bf16(o[m][2], o[m][3]);
;                     *(u32x2*)(Aout + (size_t)(row0 + ai * 128 + m) * FH + hc0 + 4 * n) = w; } } }
	v_pk_add_f32 v[200:201], v[200:201], 1.0 op_sel_hi:[1,0]
	v_rcp_f32_e32 v200, v200
	v_rcp_f32_e32 v201, v201
	v_or_b32_e32 v193, 1, v246
	v_pk_mul_f32 v[198:199], v[198:199], v[200:201]
	s_nop 0
	v_pk_mul_f32 v[196:197], v[196:197], v[198:199]
	v_pk_fma_f32 v[198:199], v[128:129], v[184:185], v[188:189]
	v_cvt_pk_bf16_f32 v250, v196, v197
	v_pk_fma_f32 v[198:199], v[132:133], v[180:181], v[198:199]
	v_mad_i64_i32 v[196:197], s[40:41], v193, s76, v[206:207]
	v_pk_fma_f32 v[152:153], v[152:153], v[176:177], v[198:199]
	v_lshl_add_u64 v[196:197], v[196:197], 0, v[204:205]
	v_exp_f32_e32 v193, v152
	v_exp_f32_e32 v198, v153
	v_add_f32_e32 v193, 1.0, v193
	v_rcp_f32_e32 v194, v193
	v_add_f32_e32 v193, 1.0, v198
	v_rcp_f32_e32 v195, v193
	v_pk_fma_f32 v[198:199], v[136:137], v[168:169], v[172:173]
	v_pk_fma_f32 v[128:129], v[128:129], v[180:181], v[140:141]
	v_pk_fma_f32 v[198:199], v[144:145], v[164:165], v[198:199]
	v_pk_fma_f32 v[128:129], v[132:133], v[176:177], v[128:129]
	v_pk_fma_f32 v[156:157], v[156:157], v[160:161], v[198:199]
	v_pk_mul_f32 v[152:153], v[152:153], v[194:195]
	v_pk_mul_f32 v[152:153], v[156:157], v[152:153]
	v_pk_fma_f32 v[156:157], v[130:131], v[186:187], v[190:191]
	v_exp_f32_e32 v140, v128
	v_pk_fma_f32 v[132:133], v[142:143], v[186:187], v[190:191]
	v_pk_fma_f32 v[156:157], v[134:135], v[182:183], v[156:157]
	v_pk_fma_f32 v[130:131], v[130:131], v[182:183], v[132:133]
	v_pk_fma_f32 v[154:155], v[154:155], v[178:179], v[156:157]
	v_pk_fma_f32 v[130:131], v[134:135], v[178:179], v[130:131]
	v_exp_f32_e32 v157, v154
	v_exp_f32_e32 v141, v129
	v_exp_f32_e32 v132, v130
	v_exp_f32_e32 v133, v131
	v_exp_f32_e32 v193, v155
	v_pk_add_f32 v[140:141], v[140:141], 1.0 op_sel_hi:[1,0]
	v_pk_add_f32 v[132:133], v[132:133], 1.0 op_sel_hi:[1,0]
	v_cvt_pk_bf16_f32 v254, v152, v153
	v_add_f32_e32 v152, 1.0, v157
	v_add_f32_e32 v153, 1.0, v193
	v_rcp_f32_e32 v140, v140
	v_rcp_f32_e32 v141, v141
	v_rcp_f32_e32 v132, v132
	v_rcp_f32_e32 v133, v133
	v_rcp_f32_e32 v152, v152
	v_rcp_f32_e32 v153, v153
	v_pk_fma_f32 v[142:143], v[150:151], v[170:171], v[174:175]
	v_pk_fma_f32 v[194:195], v[138:139], v[170:171], v[174:175]
	v_pk_fma_f32 v[136:137], v[136:137], v[164:165], v[148:149]
	v_pk_fma_f32 v[134:135], v[138:139], v[166:167], v[142:143]
	v_pk_fma_f32 v[194:195], v[146:147], v[166:167], v[194:195]
	v_pk_fma_f32 v[136:137], v[144:145], v[160:161], v[136:137]
	v_pk_mul_f32 v[128:129], v[128:129], v[140:141]
	v_pk_fma_f32 v[134:135], v[146:147], v[162:163], v[134:135]
	v_pk_mul_f32 v[130:131], v[130:131], v[132:133]
	v_pk_fma_f32 v[158:159], v[158:159], v[162:163], v[194:195]
	v_pk_mul_f32 v[152:153], v[154:155], v[152:153]
	v_pk_mul_f32 v[128:129], v[136:137], v[128:129]
	v_pk_mul_f32 v[130:131], v[134:135], v[130:131]
	v_pk_mul_f32 v[152:153], v[158:159], v[152:153]
	v_cvt_pk_bf16_f32 v251, v128, v129
	v_cvt_pk_bf16_f32 v253, v130, v131
	v_or_b32_e32 v130, 3, v246
	v_cvt_pk_bf16_f32 v255, v152, v153
	v_or_b32_e32 v152, 2, v246
	v_mad_i64_i32 v[130:131], s[40:41], v130, s76, v[206:207]
	v_mad_i64_i32 v[152:153], s[40:41], v152, s76, v[206:207]
	v_lshl_add_u64 v[140:141], v[130:131], 0, v[204:205]
	v_lshl_add_u64 v[152:153], v[152:153], 0, v[204:205]
	v_mov_b32_e32 v193, 0
	v_mov_b64_e32 v[194:195], 0
	v_mov_b64_e32 v[136:137], 0
	v_mov_b64_e32 v[138:139], 0
	v_mov_b64_e32 v[128:129], 0
	v_mov_b64_e32 v[130:131], 0
	v_mov_b64_e32 v[132:133], 0
	v_mov_b64_e32 v[134:135], 0
	s_and_saveexec_b64 s[40:41], s[28:29]
	s_cbranch_execz .LBB0_769
	ds_read_b128 v[132:135], v237 offset:2048
	ds_read_b128 v[136:139], v237 offset:2560
	ds_read_b128 v[128:131], v237 offset:3072
	ds_read_b128 v[192:195], v237 offset:3584

; #define LAS __attribute__((address_space(3)))
;     __device__ __forceinline__ void operator()(AccRef acc, const Unit& u, int wr, int wc, int fr, int fq) const {
;     ...
;         { const float* cv = cw + 128 * u.pn + clb; const float* cg = cv + FH; const float* bp = cb + 128 * u.pn + clb;
;           cwv[0][0] = *(const f32x4*)(cv); cwv[0][1] = *(const f32x4*)(cv + F2); cwv[0][2] = *(const f32x4*)(cv + 2 * F2); cwv[0][3] = *(const f32x4*)(bp);
;           cwv[0][4] = *(const f32x4*)(cg); cwv[0][5] = *(const f32x4*)(cg + F2); cwv[0][6] = *(const f32x4*)(cg + 2 * F2); cwv[0][7] = *(const f32x4*)(bp + FH); }
;         if (fr == 15) {
; #pragma unroll
;             for (int ai = 0; ai < 2; ++ai)
; #pragma unroll
;                 for (int bj = 0; bj < 2; ++bj)
; #pragma unroll
;                     for (int n = 0; n < 2; ++n) { *(LAS f32x4*)(xch + ((ai * 2 + wr) * 2 + 0) * 256 + bj * 128 + clb + 4 * n) = acc[ai][bj][2][n]; *(LAS f32x4*)(xch + ((ai * 2 + wr) * 2 + 1) * 256 + bj * 128 + clb + 4 * n) = acc[ai][bj][3][n]; }
;         }
;         float* rawu = raw + (size_t)(u.pm * 22 + u.pn) * 1024;
;         if (wr == 0 && fr == 0) {
; #pragma unroll
;             for (int bj = 0; bj < 2; ++bj)
; #pragma unroll
;                 for (int n = 0; n < 2; ++n) { *(f32x4*)(rawu + 0 * 256 + bj * 128 + clb + 4 * n) = acc[0][bj][0][n]; *(f32x4*)(rawu + 1 * 256 + bj * 128 + clb + 4 * n) = acc[0][bj][1][n]; }
;         }
;         if (wr == 1 && fr == 15) {
; #pragma unroll
;             for (int bj = 0; bj < 2; ++bj)
; #pragma unroll
;                 for (int n = 0; n < 2; ++n) { *(f32x4*)(rawu + 2 * 256 + bj * 128 + clb + 4 * n) = acc[1][bj][2][n]; *(f32x4*)(rawu + 3 * 256 + bj * 128 + clb + 4 * n) = acc[1][bj][3][n]; }
;         }
;         asm volatile("s_waitcnt lgkmcnt(0)" ::: "memory"); __builtin_amdgcn_s_barrier(); __builtin_amdgcn_s_barrier(); asm volatile("" ::: "memory");
.Lcw1359_nostage:
	v_and_b32_e32 v253, 0xf0, v219
	v_lshlrev_b32_e32 v253, 4, v253
	v_add_u32_e32 v253, 0x22000, v253
	ds_read_b128 v[160:163], v253
	ds_read_b128 v[164:167], v253 offset:16
	ds_read_b128 v[168:171], v253 offset:32
	ds_read_b128 v[172:175], v253 offset:48
	ds_read_b128 v[176:179], v253 offset:64
	ds_read_b128 v[180:183], v253 offset:80
	ds_read_b128 v[184:187], v253 offset:96
	ds_read_b128 v[188:191], v253 offset:112
	ds_read_b128 v[96:99], v253 offset:128
	ds_read_b128 v[100:103], v253 offset:144
	ds_read_b128 v[104:107], v253 offset:160
	ds_read_b128 v[108:111], v253 offset:176
	ds_read_b128 v[112:115], v253 offset:192
	ds_read_b128 v[116:119], v253 offset:208
	ds_read_b128 v[120:123], v253 offset:224
	ds_read_b128 v[124:127], v253 offset:240
	s_waitcnt lgkmcnt(0)
	v_lshlrev_b32_e32 v253, 2, v218
	s_and_saveexec_b64 s[48:49], s[12:13]
	s_cbranch_execz .LBB0_1364
	global_store_dwordx4 v253, v[156:159], s[46:47]
	global_store_dwordx4 v253, v[144:147], s[46:47] offset:1024
	global_store_dwordx4 v253, v[60:63], s[46:47] offset:16
	global_store_dwordx4 v253, v[48:51], s[46:47] offset:1040
	global_store_dwordx4 v253, v[152:155], s[46:47] offset:512
	global_store_dwordx4 v253, v[132:135], s[46:47] offset:1536
	global_store_dwordx4 v253, v[56:59], s[46:47] offset:528
	global_store_dwordx4 v253, v[36:39], s[46:47] offset:1552

; #define LAS __attribute__((address_space(3)))
;     __device__ __forceinline__ void operator()(AccRef acc, const Unit& u, int wr, int wc, int fr, int fq) const {
;     ...
;         asm volatile("s_waitcnt lgkmcnt(0)" ::: "memory"); __builtin_amdgcn_s_barrier(); __builtin_amdgcn_s_barrier(); asm volatile("" ::: "memory");
;         const int hc0 = 128 * u.pn + clb, row0 = u.pm * 256 + wr * 64 + 4 * fr;
; #pragma unroll
;         for (int n = 0; n < 2; ++n) {
;             const f32x4 w0v = cwv[n][0], w1v = cwv[n][1], w2v = cwv[n][2], bvv = cwv[n][3], w0g = cwv[n][4], w1g = cwv[n][5], w2g = cwv[n][6], bvg = cwv[n][7];
; #pragma unroll
;             for (int ai = 0; ai < 2; ++ai) {
;                 if (n == 0 && ai == 0) {
;                     asm volatile("" ::: "memory");
;                     const float* cv = cw + hc0 + 4; const float* cg = cv + FH; const float* bp = cb + hc0 + 4;
;                     cwv[1][0] = *(const f32x4*)(cv); cwv[1][1] = *(const f32x4*)(cv + F2); cwv[1][2] = *(const f32x4*)(cv + 2 * F2); cwv[1][3] = *(const f32x4*)(bp);
;                     cwv[1][4] = *(const f32x4*)(cg); cwv[1][5] = *(const f32x4*)(cg + F2); cwv[1][6] = *(const f32x4*)(cg + 2 * F2); cwv[1][7] = *(const f32x4*)(bp + FH);
;                     asm volatile("" ::: "memory"); }
;                 f32x4 h2v = (f32x4){0.f, 0.f, 0.f, 0.f}, h3v = h2v, h2g = h2v, h3g = h2v;
;                 const int pb = ai * 2 + wr - 1;
;                 if (pb >= 0 && fr == 0) { const LAS float* xp = xch + (pb * 2) * 256 + clb + 4 * n;
;                     h2v = *(const LAS f32x4*)(xp); h3v = *(const LAS f32x4*)(xp + 256); h2g = *(const LAS f32x4*)(xp + 128); h3g = *(const LAS f32x4*)(xp + 256 + 128); }
;                 float o[4][4];
; #pragma unroll
;                 for (int j = 0; j < 4; ++j) {
;                     const float v0 = acc[ai][0][0][n][j], v1 = acc[ai][0][1][n][j], v2 = acc[ai][0][2][n][j], v3 = acc[ai][0][3][n][j];
;                     const float g0 = acc[ai][1][0][n][j], g1 = acc[ai][1][1][n][j], g2 = acc[ai][1][2][n][j], g3 = acc[ai][1][3][n][j];
;                     const float pv3 = dpp_upd<0x111>(h3v[j], v3), pv2 = dpp_upd<0x111>(h2v[j], v2), pg3 = dpp_upd<0x111>(h3g[j], g3), pg2 = dpp_upd<0x111>(h2g[j], g2);
;                     const float hv0 = bvv[j] + w2v[j] * v0 + w1v[j] * pv3 + w0v[j] * pv2, hv1 = bvv[j] + w2v[j] * v1 + w1v[j] * v0 + w0v[j] * pv3;
.LBB0_1366:
	s_or_b64 exec, exec, s[48:49]
	s_barrier
	v_pk_fma_f32 v[248:249], v[152:153], v[184:185], v[188:189]
	v_mov_b32_dpp v206, v128 row_shr:1 row_mask:0xf bank_mask:0xf
	v_mov_b32_dpp v207, v129 row_shr:1 row_mask:0xf bank_mask:0xf
	v_pk_fma_f32 v[248:249], v[180:181], v[198:199], v[248:249]
	v_mov_b32_dpp v194, v148 row_shr:1 row_mask:0xf bank_mask:0xf
	v_pk_fma_f32 v[206:207], v[176:177], v[206:207], v[248:249]
	v_mov_b32_dpp v195, v149 row_shr:1 row_mask:0xf bank_mask:0xf
	v_exp_f32_e32 v248, v206
	v_exp_f32_e32 v249, v207
	v_pk_fma_f32 v[250:251], v[156:157], v[168:169], v[172:173]
	v_pk_add_f32 v[248:249], v[248:249], 1.0 op_sel_hi:[1,0]
	v_rcp_f32_e32 v248, v248
	v_rcp_f32_e32 v249, v249
	v_mov_b32_dpp v202, v136 row_shr:1 row_mask:0xf bank_mask:0xf
	v_mov_b32_dpp v203, v137 row_shr:1 row_mask:0xf bank_mask:0xf
	v_pk_fma_f32 v[250:251], v[164:165], v[194:195], v[250:251]
	v_pk_mul_f32 v[206:207], v[206:207], v[248:249]
	v_pk_fma_f32 v[202:203], v[160:161], v[202:203], v[250:251]
	v_mov_b32_dpp v200, v142 row_shr:1 row_mask:0xf bank_mask:0xf
	v_mov_b32_dpp v201, v143 row_shr:1 row_mask:0xf bank_mask:0xf
	v_pk_mul_f32 v[202:203], v[202:203], v[206:207]
	v_pk_fma_f32 v[206:207], v[154:155], v[186:187], v[190:191]
	v_mov_b32_dpp v208, v130 row_shr:1 row_mask:0xf bank_mask:0xf
	v_mov_b32_dpp v209, v131 row_shr:1 row_mask:0xf bank_mask:0xf
	v_pk_fma_f32 v[206:207], v[182:183], v[200:201], v[206:207]
	v_mov_b32_dpp v196, v150 row_shr:1 row_mask:0xf bank_mask:0xf
	v_pk_fma_f32 v[206:207], v[178:179], v[208:209], v[206:207]
	v_mov_b32_dpp v197, v151 row_shr:1 row_mask:0xf bank_mask:0xf
	v_exp_f32_e32 v193, v206
	v_exp_f32_e32 v209, v207
	v_cvt_pk_bf16_f32 v247, v202, v203
	v_add_f32_e32 v193, 1.0, v193
	v_rcp_f32_e32 v202, v193
	v_add_f32_e32 v193, 1.0, v209
	v_rcp_f32_e32 v203, v193
	v_pk_fma_f32 v[248:249], v[158:159], v[170:171], v[174:175]
	v_mov_b32_dpp v204, v138 row_shr:1 row_mask:0xf bank_mask:0xf
	v_mov_b32_dpp v205, v139 row_shr:1 row_mask:0xf bank_mask:0xf
	v_pk_fma_f32 v[248:249], v[166:167], v[196:197], v[248:249]
	v_pk_mul_f32 v[202:203], v[206:207], v[202:203]
	v_pk_fma_f32 v[204:205], v[162:163], v[204:205], v[248:249]
	v_lshl_add_u32 v246, s42, 8, v236
	v_pk_mul_f32 v[202:203], v[204:205], v[202:203]
	v_lshlrev_b64 v[204:205], 1, v[232:233]
	v_pk_fma_f32 v[232:233], v[132:133], v[184:185], v[188:189]
	v_mov_b64_e32 v[206:207], s[60:61]
	v_pk_fma_f32 v[232:233], v[152:153], v[180:181], v[232:233]
	v_cvt_pk_bf16_f32 v248, v202, v203
	v_pk_fma_f32 v[198:199], v[176:177], v[198:199], v[232:233]
	v_mad_i64_i32 v[202:203], s[42:43], v246, s82, v[206:207]
	v_exp_f32_e32 v193, v198
	v_exp_f32_e32 v232, v199
	v_lshl_add_u64 v[202:203], v[202:203], 0, v[204:205]
	v_add_f32_e32 v193, 1.0, v193
	v_rcp_f32_e32 v208, v193
	v_add_f32_e32 v193, 1.0, v232
	v_rcp_f32_e32 v209, v193
	v_pk_fma_f32 v[232:233], v[144:145], v[168:169], v[172:173]
	v_pk_fma_f32 v[140:141], v[140:141], v[184:185], v[188:189]
	v_pk_fma_f32 v[232:233], v[156:157], v[164:165], v[232:233]
	v_pk_mul_f32 v[198:199], v[198:199], v[208:209]
	v_pk_fma_f32 v[194:195], v[160:161], v[194:195], v[232:233]
	v_pk_fma_f32 v[208:209], v[146:147], v[170:171], v[174:175]
	v_pk_mul_f32 v[194:195], v[194:195], v[198:199]
	v_pk_fma_f32 v[198:199], v[134:135], v[186:187], v[190:191]
	v_pk_fma_f32 v[208:209], v[158:159], v[166:167], v[208:209]
	v_pk_fma_f32 v[198:199], v[154:155], v[182:183], v[198:199]
	v_pk_fma_f32 v[196:197], v[162:163], v[196:197], v[208:209]
	v_pk_fma_f32 v[198:199], v[178:179], v[200:201], v[198:199]
	v_cvt_pk_bf16_f32 v249, v194, v195
	v_exp_f32_e32 v200, v198
	v_exp_f32_e32 v201, v199
	v_pk_fma_f32 v[148:149], v[148:149], v[168:169], v[172:173]
; #define LAS __attribute__((address_space(3)))
; __device__ __forceinline__ float sigmoidf_(float x) { return __builtin_amdgcn_rcpf(1.0f + __expf(-x)); }
;     __device__ __forceinline__ void operator()(AccRef acc, const Unit& u, int wr, int wc, int fr, int fq) const {
;     ...
;                 f32x4 h2v = (f32x4){0.f, 0.f, 0.f, 0.f}, h3v = h2v, h2g = h2v, h3g = h2v;
;                 const int pb = ai * 2 + wr - 1;
;                 if (pb >= 0 && fr == 0) { const LAS float* xp = xch + (pb * 2) * 256 + clb + 4 * n;
;                     h2v = *(const LAS f32x4*)(xp); h3v = *(const LAS f32x4*)(xp + 256); h2g = *(const LAS f32x4*)(xp + 128); h3g = *(const LAS f32x4*)(xp + 256 + 128); }
;                 float o[4][4];
; #pragma unroll
;                 for (int j = 0; j < 4; ++j) {
;                     const float v0 = acc[ai][0][0][n][j], v1 = acc[ai][0][1][n][j], v2 = acc[ai][0][2][n][j], v3 = acc[ai][0][3][n][j];
;                     const float g0 = acc[ai][1][0][n][j], g1 = acc[ai][1][1][n][j], g2 = acc[ai][1][2][n][j], g3 = acc[ai][1][3][n][j];
;                     const float pv3 = dpp_upd<0x111>(h3v[j], v3), pv2 = dpp_upd<0x111>(h2v[j], v2), pg3 = dpp_upd<0x111>(h3g[j], g3), pg2 = dpp_upd<0x111>(h2g[j], g2);
;                     const float hv0 = bvv[j] + w2v[j] * v0 + w1v[j] * pv3 + w0v[j] * pv2, hv1 = bvv[j] + w2v[j] * v1 + w1v[j] * v0 + w0v[j] * pv3;
;                     const float hv2 = bvv[j] + w2v[j] * v2 + w1v[j] * v1 + w0v[j] * v0, hv3 = bvv[j] + w2v[j] * v3 + w1v[j] * v2 + w0v[j] * v1;
;                     const float hg0 = bvg[j] + w2g[j] * g0 + w1g[j] * pg3 + w0g[j] * pg2, hg1 = bvg[j] + w2g[j] * g1 + w1g[j] * g0 + w0g[j] * pg3;
;                     const float hg2 = bvg[j] + w2g[j] * g2 + w1g[j] * g1 + w0g[j] * g0, hg3 = bvg[j] + w2g[j] * g3 + w1g[j] * g2 + w0g[j] * g1;
;                     o[0][j] = hg0 * sigmoidf_(hg0) * hv0; o[1][j] = hg1 * sigmoidf_(hg1) * hv1; o[2][j] = hg2 * sigmoidf_(hg2) * hv2; o[3][j] = hg3 * sigmoidf_(hg3) * hv3; }
; #pragma unroll
;                 for (int m = 0; m < 4; ++m) { u32x2 w; w.x = cvt_pk_bf16(o[m][0], o[m][1]); w.y = cvt_pk_bf16(o[m][2], o[m][3]);
;                     *(u32x2*)(Aout + (size_t)(row0 + ai * 128 + m) * FH + hc0 + 4 * n) = w; } } }
	v_pk_add_f32 v[200:201], v[200:201], 1.0 op_sel_hi:[1,0]
	v_rcp_f32_e32 v200, v200
	v_rcp_f32_e32 v201, v201
	v_or_b32_e32 v193, 1, v246
	v_pk_mul_f32 v[198:199], v[198:199], v[200:201]
	s_nop 0
	v_pk_mul_f32 v[196:197], v[196:197], v[198:199]
	v_pk_fma_f32 v[198:199], v[128:129], v[184:185], v[188:189]
	v_cvt_pk_bf16_f32 v250, v196, v197
	v_pk_fma_f32 v[198:199], v[132:133], v[180:181], v[198:199]
	v_mad_i64_i32 v[196:197], s[42:43], v193, s82, v[206:207]
	v_pk_fma_f32 v[152:153], v[152:153], v[176:177], v[198:199]
	v_lshl_add_u64 v[196:197], v[196:197], 0, v[204:205]
	v_exp_f32_e32 v193, v152
	v_exp_f32_e32 v198, v153
	v_add_f32_e32 v193, 1.0, v193
	v_rcp_f32_e32 v194, v193
	v_add_f32_e32 v193, 1.0, v198
	v_rcp_f32_e32 v195, v193
	v_pk_fma_f32 v[198:199], v[136:137], v[168:169], v[172:173]
	v_pk_fma_f32 v[128:129], v[128:129], v[180:181], v[140:141]
	v_pk_fma_f32 v[198:199], v[144:145], v[164:165], v[198:199]
	v_pk_fma_f32 v[128:129], v[132:133], v[176:177], v[128:129]
	v_pk_fma_f32 v[156:157], v[156:157], v[160:161], v[198:199]
	v_pk_mul_f32 v[152:153], v[152:153], v[194:195]
	v_pk_mul_f32 v[152:153], v[156:157], v[152:153]
	v_pk_fma_f32 v[156:157], v[130:131], v[186:187], v[190:191]
	v_exp_f32_e32 v140, v128
	v_pk_fma_f32 v[132:133], v[142:143], v[186:187], v[190:191]
	v_pk_fma_f32 v[156:157], v[134:135], v[182:183], v[156:157]
	v_pk_fma_f32 v[130:131], v[130:131], v[182:183], v[132:133]
	v_pk_fma_f32 v[154:155], v[154:155], v[178:179], v[156:157]
	v_pk_fma_f32 v[130:131], v[134:135], v[178:179], v[130:131]
	v_exp_f32_e32 v157, v154
	v_exp_f32_e32 v141, v129
	v_exp_f32_e32 v132, v130
	v_exp_f32_e32 v133, v131
	v_exp_f32_e32 v193, v155
	v_pk_add_f32 v[140:141], v[140:141], 1.0 op_sel_hi:[1,0]
	v_pk_add_f32 v[132:133], v[132:133], 1.0 op_sel_hi:[1,0]
	v_cvt_pk_bf16_f32 v254, v152, v153
	v_add_f32_e32 v152, 1.0, v157
	v_add_f32_e32 v153, 1.0, v193
	v_rcp_f32_e32 v140, v140
	v_rcp_f32_e32 v141, v141
	v_rcp_f32_e32 v132, v132
	v_rcp_f32_e32 v133, v133
	v_rcp_f32_e32 v152, v152
	v_rcp_f32_e32 v153, v153
	v_pk_fma_f32 v[142:143], v[150:151], v[170:171], v[174:175]
	v_pk_fma_f32 v[194:195], v[138:139], v[170:171], v[174:175]
	v_pk_fma_f32 v[136:137], v[136:137], v[164:165], v[148:149]
	v_pk_fma_f32 v[134:135], v[138:139], v[166:167], v[142:143]
	v_pk_fma_f32 v[194:195], v[146:147], v[166:167], v[194:195]
	v_pk_fma_f32 v[136:137], v[144:145], v[160:161], v[136:137]
	v_pk_mul_f32 v[128:129], v[128:129], v[140:141]
	v_pk_fma_f32 v[134:135], v[146:147], v[162:163], v[134:135]
	v_pk_mul_f32 v[130:131], v[130:131], v[132:133]
	v_pk_fma_f32 v[158:159], v[158:159], v[162:163], v[194:195]
	v_pk_mul_f32 v[152:153], v[154:155], v[152:153]
	v_pk_mul_f32 v[128:129], v[136:137], v[128:129]
	v_pk_mul_f32 v[130:131], v[134:135], v[130:131]
	v_pk_mul_f32 v[152:153], v[158:159], v[152:153]
	v_cvt_pk_bf16_f32 v251, v128, v129
	v_cvt_pk_bf16_f32 v253, v130, v131
	v_or_b32_e32 v130, 3, v246
	v_cvt_pk_bf16_f32 v255, v152, v153
	v_or_b32_e32 v152, 2, v246
	v_mad_i64_i32 v[130:131], s[42:43], v130, s82, v[206:207]
	v_mad_i64_i32 v[152:153], s[42:43], v152, s82, v[206:207]
	v_lshl_add_u64 v[140:141], v[130:131], 0, v[204:205]
	v_lshl_add_u64 v[152:153], v[152:153], 0, v[204:205]
	v_mov_b32_e32 v193, 0
	v_mov_b64_e32 v[194:195], 0
	v_mov_b64_e32 v[136:137], 0
	v_mov_b64_e32 v[138:139], 0
	v_mov_b64_e32 v[128:129], 0
	v_mov_b64_e32 v[130:131], 0
	v_mov_b64_e32 v[132:133], 0
	v_mov_b64_e32 v[134:135], 0
	s_and_saveexec_b64 s[42:43], s[30:31]
	s_cbranch_execz .LBB0_1370
	ds_read_b128 v[132:135], v237 offset:2048
	ds_read_b128 v[136:139], v237 offset:2560
	ds_read_b128 v[128:131], v237 offset:3072
	ds_read_b128 v[192:195], v237 offset:3584

; #define LAS __attribute__((address_space(3)))
;     __device__ __forceinline__ void operator()(AccRef acc, const Unit& u, int wr, int wc, int fr, int fq) const {
;     ...
;         { const float* cv = cw + 128 * u.pn + clb; const float* cg = cv + FH; const float* bp = cb + 128 * u.pn + clb;
;           cwv[0][0] = *(const f32x4*)(cv); cwv[0][1] = *(const f32x4*)(cv + F2); cwv[0][2] = *(const f32x4*)(cv + 2 * F2); cwv[0][3] = *(const f32x4*)(bp);
;           cwv[0][4] = *(const f32x4*)(cg); cwv[0][5] = *(const f32x4*)(cg + F2); cwv[0][6] = *(const f32x4*)(cg + 2 * F2); cwv[0][7] = *(const f32x4*)(bp + FH); }
;         if (fr == 15) {
; #pragma unroll
;             for (int ai = 0; ai < 2; ++ai)
; #pragma unroll
;                 for (int bj = 0; bj < 2; ++bj)
; #pragma unroll
;                     for (int n = 0; n < 2; ++n) { *(LAS f32x4*)(xch + ((ai * 2 + wr) * 2 + 0) * 256 + bj * 128 + clb + 4 * n) = acc[ai][bj][2][n]; *(LAS f32x4*)(xch + ((ai * 2 + wr) * 2 + 1) * 256 + bj * 128 + clb + 4 * n) = acc[ai][bj][3][n]; }
;         }
;         float* rawu = raw + (size_t)(u.pm * 22 + u.pn) * 1024;
;         if (wr == 0 && fr == 0) {
; #pragma unroll
;             for (int bj = 0; bj < 2; ++bj)
; #pragma unroll
;                 for (int n = 0; n < 2; ++n) { *(f32x4*)(rawu + 0 * 256 + bj * 128 + clb + 4 * n) = acc[0][bj][0][n]; *(f32x4*)(rawu + 1 * 256 + bj * 128 + clb + 4 * n) = acc[0][bj][1][n]; }
;         }
;         if (wr == 1 && fr == 15) {
; #pragma unroll
;             for (int bj = 0; bj < 2; ++bj)
; #pragma unroll
;                 for (int n = 0; n < 2; ++n) { *(f32x4*)(rawu + 2 * 256 + bj * 128 + clb + 4 * n) = acc[1][bj][2][n]; *(f32x4*)(rawu + 3 * 256 + bj * 128 + clb + 4 * n) = acc[1][bj][3][n]; }
;         }
;         asm volatile("s_waitcnt lgkmcnt(0)" ::: "memory"); __builtin_amdgcn_s_barrier(); __builtin_amdgcn_s_barrier(); asm volatile("" ::: "memory");
.Lcw1940_nostage:
	v_and_b32_e32 v253, 0xf0, v219
	v_lshlrev_b32_e32 v253, 4, v253
	v_add_u32_e32 v253, 0x22000, v253
	ds_read_b128 v[160:163], v253
	ds_read_b128 v[164:167], v253 offset:16
	ds_read_b128 v[168:171], v253 offset:32
	ds_read_b128 v[172:175], v253 offset:48
	ds_read_b128 v[176:179], v253 offset:64
	ds_read_b128 v[180:183], v253 offset:80
	ds_read_b128 v[184:187], v253 offset:96
	ds_read_b128 v[188:191], v253 offset:112
	ds_read_b128 v[96:99], v253 offset:128
	ds_read_b128 v[100:103], v253 offset:144
	ds_read_b128 v[104:107], v253 offset:160
	ds_read_b128 v[108:111], v253 offset:176
	ds_read_b128 v[112:115], v253 offset:192
	ds_read_b128 v[116:119], v253 offset:208
	ds_read_b128 v[120:123], v253 offset:224
	ds_read_b128 v[124:127], v253 offset:240
	s_waitcnt lgkmcnt(0)
	v_lshlrev_b32_e32 v253, 2, v218
	s_and_saveexec_b64 s[40:41], s[8:9]
	s_cbranch_execz .LBB0_1945
	global_store_dwordx4 v253, v[156:159], s[38:39]
	global_store_dwordx4 v253, v[144:147], s[38:39] offset:1024
	global_store_dwordx4 v253, v[60:63], s[38:39] offset:16
	global_store_dwordx4 v253, v[48:51], s[38:39] offset:1040
	global_store_dwordx4 v253, v[152:155], s[38:39] offset:512
	global_store_dwordx4 v253, v[132:135], s[38:39] offset:1536
	global_store_dwordx4 v253, v[56:59], s[38:39] offset:528
	global_store_dwordx4 v253, v[36:39], s[38:39] offset:1552

; #define LAS __attribute__((address_space(3)))
;     __device__ __forceinline__ void operator()(AccRef acc, const Unit& u, int wr, int wc, int fr, int fq) const {
;     ...
;         asm volatile("s_waitcnt lgkmcnt(0)" ::: "memory"); __builtin_amdgcn_s_barrier(); __builtin_amdgcn_s_barrier(); asm volatile("" ::: "memory");
;         const int hc0 = 128 * u.pn + clb, row0 = u.pm * 256 + wr * 64 + 4 * fr;
; #pragma unroll
;         for (int n = 0; n < 2; ++n) {
;             const f32x4 w0v = cwv[n][0], w1v = cwv[n][1], w2v = cwv[n][2], bvv = cwv[n][3], w0g = cwv[n][4], w1g = cwv[n][5], w2g = cwv[n][6], bvg = cwv[n][7];
; #pragma unroll
;             for (int ai = 0; ai < 2; ++ai) {
;                 if (n == 0 && ai == 0) {
;                     asm volatile("" ::: "memory");
;                     const float* cv = cw + hc0 + 4; const float* cg = cv + FH; const float* bp = cb + hc0 + 4;
;                     cwv[1][0] = *(const f32x4*)(cv); cwv[1][1] = *(const f32x4*)(cv + F2); cwv[1][2] = *(const f32x4*)(cv + 2 * F2); cwv[1][3] = *(const f32x4*)(bp);
;                     cwv[1][4] = *(const f32x4*)(cg); cwv[1][5] = *(const f32x4*)(cg + F2); cwv[1][6] = *(const f32x4*)(cg + 2 * F2); cwv[1][7] = *(const f32x4*)(bp + FH);
;                     asm volatile("" ::: "memory"); }
;                 f32x4 h2v = (f32x4){0.f, 0.f, 0.f, 0.f}, h3v = h2v, h2g = h2v, h3g = h2v;
;                 const int pb = ai * 2 + wr - 1;
;                 if (pb >= 0 && fr == 0) { const LAS float* xp = xch + (pb * 2) * 256 + clb + 4 * n;
;                     h2v = *(const LAS f32x4*)(xp); h3v = *(const LAS f32x4*)(xp + 256); h2g = *(const LAS f32x4*)(xp + 128); h3g = *(const LAS f32x4*)(xp + 256 + 128); }
;                 float o[4][4];
; #pragma unroll
;                 for (int j = 0; j < 4; ++j) {
;                     const float v0 = acc[ai][0][0][n][j], v1 = acc[ai][0][1][n][j], v2 = acc[ai][0][2][n][j], v3 = acc[ai][0][3][n][j];
;                     const float g0 = acc[ai][1][0][n][j], g1 = acc[ai][1][1][n][j], g2 = acc[ai][1][2][n][j], g3 = acc[ai][1][3][n][j];
;                     const float pv3 = dpp_upd<0x111>(h3v[j], v3), pv2 = dpp_upd<0x111>(h2v[j], v2), pg3 = dpp_upd<0x111>(h3g[j], g3), pg2 = dpp_upd<0x111>(h2g[j], g2);
;                     const float hv0 = bvv[j] + w2v[j] * v0 + w1v[j] * pv3 + w0v[j] * pv2, hv1 = bvv[j] + w2v[j] * v1 + w1v[j] * v0 + w0v[j] * pv3;
.LBB0_1947:
	s_or_b64 exec, exec, s[40:41]
	s_barrier
	v_pk_fma_f32 v[246:247], v[152:153], v[184:185], v[188:189]
	v_mov_b32_dpp v206, v128 row_shr:1 row_mask:0xf bank_mask:0xf
	v_mov_b32_dpp v207, v129 row_shr:1 row_mask:0xf bank_mask:0xf
	v_pk_fma_f32 v[246:247], v[180:181], v[198:199], v[246:247]
	v_mov_b32_dpp v194, v148 row_shr:1 row_mask:0xf bank_mask:0xf
	v_pk_fma_f32 v[206:207], v[176:177], v[206:207], v[246:247]
	v_mov_b32_dpp v195, v149 row_shr:1 row_mask:0xf bank_mask:0xf
	v_exp_f32_e32 v246, v206
	v_exp_f32_e32 v247, v207
	v_pk_fma_f32 v[248:249], v[156:157], v[168:169], v[172:173]
	v_pk_add_f32 v[246:247], v[246:247], 1.0 op_sel_hi:[1,0]
	v_rcp_f32_e32 v246, v246
	v_rcp_f32_e32 v247, v247
	v_mov_b32_dpp v202, v136 row_shr:1 row_mask:0xf bank_mask:0xf
	v_mov_b32_dpp v203, v137 row_shr:1 row_mask:0xf bank_mask:0xf
	v_pk_fma_f32 v[248:249], v[164:165], v[194:195], v[248:249]
	v_pk_mul_f32 v[206:207], v[206:207], v[246:247]
	v_pk_fma_f32 v[202:203], v[160:161], v[202:203], v[248:249]
	v_mov_b32_dpp v200, v142 row_shr:1 row_mask:0xf bank_mask:0xf
	v_mov_b32_dpp v201, v143 row_shr:1 row_mask:0xf bank_mask:0xf
	v_pk_mul_f32 v[202:203], v[202:203], v[206:207]
	v_pk_fma_f32 v[206:207], v[154:155], v[186:187], v[190:191]
	v_mov_b32_dpp v208, v130 row_shr:1 row_mask:0xf bank_mask:0xf
	v_mov_b32_dpp v209, v131 row_shr:1 row_mask:0xf bank_mask:0xf
	v_pk_fma_f32 v[206:207], v[182:183], v[200:201], v[206:207]
	v_mov_b32_dpp v196, v150 row_shr:1 row_mask:0xf bank_mask:0xf
	v_pk_fma_f32 v[206:207], v[178:179], v[208:209], v[206:207]
	v_mov_b32_dpp v197, v151 row_shr:1 row_mask:0xf bank_mask:0xf
	v_exp_f32_e32 v193, v206
	v_exp_f32_e32 v209, v207
	v_cvt_pk_bf16_f32 v208, v202, v203
	v_add_f32_e32 v193, 1.0, v193
	v_rcp_f32_e32 v202, v193
	v_add_f32_e32 v193, 1.0, v209
	v_rcp_f32_e32 v203, v193
	v_pk_fma_f32 v[246:247], v[158:159], v[170:171], v[174:175]
	v_mov_b32_dpp v204, v138 row_shr:1 row_mask:0xf bank_mask:0xf
	v_mov_b32_dpp v205, v139 row_shr:1 row_mask:0xf bank_mask:0xf
	v_pk_fma_f32 v[246:247], v[166:167], v[196:197], v[246:247]
	v_pk_mul_f32 v[202:203], v[206:207], v[202:203]
	v_pk_fma_f32 v[204:205], v[162:163], v[204:205], v[246:247]
	v_lshl_add_u32 v245, s34, 8, v235
	v_pk_mul_f32 v[202:203], v[204:205], v[202:203]
	v_lshlrev_b64 v[204:205], 1, v[232:233]
	v_pk_fma_f32 v[232:233], v[132:133], v[184:185], v[188:189]
	v_mov_b64_e32 v[206:207], s[60:61]
	v_pk_fma_f32 v[232:233], v[152:153], v[180:181], v[232:233]
	v_cvt_pk_bf16_f32 v247, v202, v203
	v_pk_fma_f32 v[198:199], v[176:177], v[198:199], v[232:233]
	v_mad_i64_i32 v[202:203], s[34:35], v245, s63, v[206:207]
	v_exp_f32_e32 v193, v198
	v_exp_f32_e32 v232, v199
	v_lshl_add_u64 v[202:203], v[202:203], 0, v[204:205]
	v_add_f32_e32 v193, 1.0, v193
	v_mov_b32_e32 v246, v208
	v_rcp_f32_e32 v208, v193
	v_add_f32_e32 v193, 1.0, v232
	v_rcp_f32_e32 v209, v193
	v_pk_fma_f32 v[232:233], v[144:145], v[168:169], v[172:173]
	v_pk_fma_f32 v[140:141], v[140:141], v[184:185], v[188:189]
	v_pk_fma_f32 v[232:233], v[156:157], v[164:165], v[232:233]
	v_pk_mul_f32 v[198:199], v[198:199], v[208:209]
	v_pk_fma_f32 v[194:195], v[160:161], v[194:195], v[232:233]
	v_pk_fma_f32 v[208:209], v[146:147], v[170:171], v[174:175]
	v_pk_mul_f32 v[194:195], v[194:195], v[198:199]
	v_pk_fma_f32 v[198:199], v[134:135], v[186:187], v[190:191]
	v_pk_fma_f32 v[208:209], v[158:159], v[166:167], v[208:209]
	v_pk_fma_f32 v[198:199], v[154:155], v[182:183], v[198:199]
	v_pk_fma_f32 v[196:197], v[162:163], v[196:197], v[208:209]
	v_pk_fma_f32 v[198:199], v[178:179], v[200:201], v[198:199]
	v_cvt_pk_bf16_f32 v248, v194, v195
	v_exp_f32_e32 v200, v198
	v_exp_f32_e32 v201, v199
	v_pk_fma_f32 v[148:149], v[148:149], v[168:169], v[172:173]
; #define LAS __attribute__((address_space(3)))
; __device__ __forceinline__ float sigmoidf_(float x) { return __builtin_amdgcn_rcpf(1.0f + __expf(-x)); }
;     __device__ __forceinline__ void operator()(AccRef acc, const Unit& u, int wr, int wc, int fr, int fq) const {
;     ...
;                 f32x4 h2v = (f32x4){0.f, 0.f, 0.f, 0.f}, h3v = h2v, h2g = h2v, h3g = h2v;
;                 const int pb = ai * 2 + wr - 1;
;                 if (pb >= 0 && fr == 0) { const LAS float* xp = xch + (pb * 2) * 256 + clb + 4 * n;
;                     h2v = *(const LAS f32x4*)(xp); h3v = *(const LAS f32x4*)(xp + 256); h2g = *(const LAS f32x4*)(xp + 128); h3g = *(const LAS f32x4*)(xp + 256 + 128); }
;                 float o[4][4];
; #pragma unroll
;                 for (int j = 0; j < 4; ++j) {
;                     const float v0 = acc[ai][0][0][n][j], v1 = acc[ai][0][1][n][j], v2 = acc[ai][0][2][n][j], v3 = acc[ai][0][3][n][j];
;                     const float g0 = acc[ai][1][0][n][j], g1 = acc[ai][1][1][n][j], g2 = acc[ai][1][2][n][j], g3 = acc[ai][1][3][n][j];
;                     const float pv3 = dpp_upd<0x111>(h3v[j], v3), pv2 = dpp_upd<0x111>(h2v[j], v2), pg3 = dpp_upd<0x111>(h3g[j], g3), pg2 = dpp_upd<0x111>(h2g[j], g2);
;                     const float hv0 = bvv[j] + w2v[j] * v0 + w1v[j] * pv3 + w0v[j] * pv2, hv1 = bvv[j] + w2v[j] * v1 + w1v[j] * v0 + w0v[j] * pv3;
;                     const float hv2 = bvv[j] + w2v[j] * v2 + w1v[j] * v1 + w0v[j] * v0, hv3 = bvv[j] + w2v[j] * v3 + w1v[j] * v2 + w0v[j] * v1;
;                     const float hg0 = bvg[j] + w2g[j] * g0 + w1g[j] * pg3 + w0g[j] * pg2, hg1 = bvg[j] + w2g[j] * g1 + w1g[j] * g0 + w0g[j] * pg3;
;                     const float hg2 = bvg[j] + w2g[j] * g2 + w1g[j] * g1 + w0g[j] * g0, hg3 = bvg[j] + w2g[j] * g3 + w1g[j] * g2 + w0g[j] * g1;
;                     o[0][j] = hg0 * sigmoidf_(hg0) * hv0; o[1][j] = hg1 * sigmoidf_(hg1) * hv1; o[2][j] = hg2 * sigmoidf_(hg2) * hv2; o[3][j] = hg3 * sigmoidf_(hg3) * hv3; }
; #pragma unroll
;                 for (int m = 0; m < 4; ++m) { u32x2 w; w.x = cvt_pk_bf16(o[m][0], o[m][1]); w.y = cvt_pk_bf16(o[m][2], o[m][3]);
;                     *(u32x2*)(Aout + (size_t)(row0 + ai * 128 + m) * FH + hc0 + 4 * n) = w; } } }
	v_pk_add_f32 v[200:201], v[200:201], 1.0 op_sel_hi:[1,0]
	v_rcp_f32_e32 v200, v200
	v_rcp_f32_e32 v201, v201
	v_or_b32_e32 v193, 1, v245
	v_pk_mul_f32 v[198:199], v[198:199], v[200:201]
	s_nop 0
	v_pk_mul_f32 v[196:197], v[196:197], v[198:199]
	v_pk_fma_f32 v[198:199], v[128:129], v[184:185], v[188:189]
	v_cvt_pk_bf16_f32 v249, v196, v197
	v_pk_fma_f32 v[198:199], v[132:133], v[180:181], v[198:199]
	v_mad_i64_i32 v[196:197], s[34:35], v193, s63, v[206:207]
	v_pk_fma_f32 v[152:153], v[152:153], v[176:177], v[198:199]
	v_lshl_add_u64 v[196:197], v[196:197], 0, v[204:205]
	v_exp_f32_e32 v193, v152
	v_exp_f32_e32 v198, v153
	v_add_f32_e32 v193, 1.0, v193
	v_rcp_f32_e32 v194, v193
	v_add_f32_e32 v193, 1.0, v198
	v_rcp_f32_e32 v195, v193
	v_pk_fma_f32 v[198:199], v[136:137], v[168:169], v[172:173]
	v_pk_fma_f32 v[128:129], v[128:129], v[180:181], v[140:141]
	v_pk_fma_f32 v[198:199], v[144:145], v[164:165], v[198:199]
	v_pk_fma_f32 v[128:129], v[132:133], v[176:177], v[128:129]
	v_pk_fma_f32 v[156:157], v[156:157], v[160:161], v[198:199]
	v_pk_mul_f32 v[152:153], v[152:153], v[194:195]
	v_pk_mul_f32 v[152:153], v[156:157], v[152:153]
	v_pk_fma_f32 v[156:157], v[130:131], v[186:187], v[190:191]
	v_exp_f32_e32 v140, v128
	v_pk_fma_f32 v[132:133], v[142:143], v[186:187], v[190:191]
	v_pk_fma_f32 v[156:157], v[134:135], v[182:183], v[156:157]
	v_pk_fma_f32 v[130:131], v[130:131], v[182:183], v[132:133]
	v_pk_fma_f32 v[154:155], v[154:155], v[178:179], v[156:157]
	v_pk_fma_f32 v[130:131], v[134:135], v[178:179], v[130:131]
	v_exp_f32_e32 v157, v154
	v_exp_f32_e32 v141, v129
	v_exp_f32_e32 v132, v130
	v_exp_f32_e32 v133, v131
	v_exp_f32_e32 v193, v155
	v_pk_add_f32 v[140:141], v[140:141], 1.0 op_sel_hi:[1,0]
	v_pk_add_f32 v[132:133], v[132:133], 1.0 op_sel_hi:[1,0]
	v_cvt_pk_bf16_f32 v253, v152, v153
	v_add_f32_e32 v152, 1.0, v157
	v_add_f32_e32 v153, 1.0, v193
	v_rcp_f32_e32 v140, v140
	v_rcp_f32_e32 v141, v141
	v_rcp_f32_e32 v132, v132
	v_rcp_f32_e32 v133, v133
	v_rcp_f32_e32 v152, v152
	v_rcp_f32_e32 v153, v153
	v_pk_fma_f32 v[142:143], v[150:151], v[170:171], v[174:175]
	v_pk_fma_f32 v[194:195], v[138:139], v[170:171], v[174:175]
	v_pk_fma_f32 v[136:137], v[136:137], v[164:165], v[148:149]
	v_pk_fma_f32 v[134:135], v[138:139], v[166:167], v[142:143]
	v_pk_fma_f32 v[194:195], v[146:147], v[166:167], v[194:195]
	v_pk_fma_f32 v[136:137], v[144:145], v[160:161], v[136:137]
	v_pk_mul_f32 v[128:129], v[128:129], v[140:141]
	v_pk_fma_f32 v[134:135], v[146:147], v[162:163], v[134:135]
	v_pk_mul_f32 v[130:131], v[130:131], v[132:133]
	v_pk_fma_f32 v[158:159], v[158:159], v[162:163], v[194:195]
	v_pk_mul_f32 v[152:153], v[154:155], v[152:153]
	v_pk_mul_f32 v[128:129], v[136:137], v[128:129]
	v_pk_mul_f32 v[130:131], v[134:135], v[130:131]
	v_pk_mul_f32 v[152:153], v[158:159], v[152:153]
	v_cvt_pk_bf16_f32 v250, v128, v129
	v_cvt_pk_bf16_f32 v251, v130, v131
	v_or_b32_e32 v130, 3, v245
	v_cvt_pk_bf16_f32 v254, v152, v153
	v_or_b32_e32 v152, 2, v245
	v_mad_i64_i32 v[130:131], s[34:35], v130, s63, v[206:207]
	v_mad_i64_i32 v[152:153], s[34:35], v152, s63, v[206:207]
	v_lshl_add_u64 v[140:141], v[130:131], 0, v[204:205]
	v_lshl_add_u64 v[152:153], v[152:153], 0, v[204:205]
	v_mov_b32_e32 v193, 0
	v_mov_b64_e32 v[194:195], 0
	v_mov_b64_e32 v[136:137], 0
	v_mov_b64_e32 v[138:139], 0
	v_mov_b64_e32 v[128:129], 0
	v_mov_b64_e32 v[130:131], 0
	v_mov_b64_e32 v[132:133], 0
	v_mov_b64_e32 v[134:135], 0
	s_and_saveexec_b64 s[34:35], s[22:23]
	s_cbranch_execz .LBB0_1951
	ds_read_b128 v[132:135], v236 offset:2048
	ds_read_b128 v[136:139], v236 offset:2560
	ds_read_b128 v[128:131], v236 offset:3072
	ds_read_b128 v[192:195], v236 offset:3584
